# GLA state item chunk loop: the four k/v/v/gate tile loads issued together with counted waits instead of four load-wait round trips
# speedup vs baseline: 1.0083x; 1.0016x over previous
; DN void gla_state_item(const Params& p, int l, int item, char* smem) {
;     ...
;   for (int c = 0; c < 36; ++c) {
;     int cs = (dir == 0) ? (c < 4 ? 32 + c : c - 4) : (c < 4 ? 35 - c : 35 - c);
;     size_t m0 = (size_t)b * TT + cs * 64;
;     vsync();
;     {
;       float t8[8];
;       { const int li = tid >> 2, d8 = (tid & 3) * 8; unpack8(*(const u32x4*)(P + (m0 + li) * PW + 2048 + hh * 32 + d8), t8);
; #pragma unroll
;         for (int e = 0; e < 8; ++e) kk_[li * 33 + d8 + e] = t8[e]; }
; #pragma unroll
;       for (int i = 0; i < 2; ++i) { const int c = tid + 256 * i, li = c >> 3, e8 = (c & 7) * 8; unpack8(*(const u32x4*)(P + (m0 + li) * PW + 2176 + hh * 64 + e8), t8);
;         *(f32x4v*)(vv + li * 64 + e8) = (f32x4v){t8[0], t8[1], t8[2], t8[3]}; *(f32x4v*)(vv + li * 64 + e8 + 4) = (f32x4v){t8[4], t8[5], t8[6], t8[7]}; }
;       if (tid < 128) { const int li = tid >> 1, q8 = (tid & 1) * 8; unpack8(*(const u32x4*)(P + (m0 + li) * PW + 2432 + dir * 16 + q8), t8);
;         *(f32x4v*)(gg + li * 16 + q8) = (f32x4v){t8[0], t8[1], t8[2], t8[3]}; *(f32x4v*)(gg + li * 16 + q8 + 4) = (f32x4v){t8[4], t8[5], t8[6], t8[7]}; }
;     }
.LBB0_426:
	s_waitcnt lgkmcnt(0)
	s_barrier
	s_cmp_lt_u32 s66, 4
	s_cselect_b32 s42, 32, -4
	s_add_i32 s56, s42, s66
	s_sub_i32 s57, 35, s66
	s_and_b64 s[42:43], s[52:53], exec
	s_cselect_b32 s56, s56, s57
	s_lshl_b32 s42, s56, 6
	s_ashr_i32 s43, s42, 31
	v_lshl_add_u64 v[44:45], v[20:21], 0, s[42:43]
	s_and_saveexec_b64 s[42:43], s[2:3]
	s_cbranch_execz .Lgla_noload
	v_lshl_add_u64 v[242:243], v[44:45], 0, v[24:25]
	v_mov_b64_e32 v[244:245], s[84:85]
	v_mad_u64_u32 v[244:245], s[58:59], v242, s88, v[244:245]
	v_mov_b32_e32 v242, v245
	v_mad_u64_u32 v[242:243], s[58:59], v243, s88, v[242:243]
	v_mov_b32_e32 v245, v242
	v_lshl_add_u64 v[242:243], v[244:245], 0, s[80:81]
	v_mov_b32_e32 v43, v153
	v_lshl_add_u64 v[242:243], v[242:243], 0, v[42:43]
	v_add_co_u32_e32 v242, vcc, 0x1000, v242
	s_nop 1
	v_addc_co_u32_e32 v243, vcc, 0, v243, vcc
	global_load_dwordx4 v[238:241], v[242:243], off offset:768
.Lgla_noload:
	s_or_b64 exec, exec, s[42:43]
	v_lshl_add_u64 v[46:47], v[44:45], 0, v[22:23]
	v_mov_b64_e32 v[50:51], s[84:85]
	v_mad_u64_u32 v[48:49], s[42:43], v46, s88, v[50:51]
	v_mov_b32_e32 v46, v49
	v_mad_u64_u32 v[46:47], s[42:43], v47, s88, v[46:47]
	v_mov_b32_e32 v49, v46
	v_lshl_add_u64 v[46:47], v[48:49], 0, v[152:153]
	v_mov_b32_e32 v37, v153
	v_lshl_add_u64 v[46:47], v[46:47], 0, v[36:37]
	v_add_co_u32_e32 v46, vcc, s96, v46
	s_nop 1
	v_addc_co_u32_e32 v47, vcc, 0, v47, vcc
	global_load_dwordx4 v[226:229], v[46:47], off
	v_lshl_add_u64 v[46:47], v[44:45], 0, v[18:19]
	v_mad_u64_u32 v[48:49], s[42:43], v46, s88, v[50:51]
	v_mov_b32_e32 v46, v49
	v_mad_u64_u32 v[46:47], s[42:43], v47, s88, v[46:47]
	v_mov_b32_e32 v49, v46
	v_mov_b32_e32 v39, v153
	v_lshl_add_u64 v[46:47], v[48:49], 0, v[38:39]
	v_mov_b32_e32 v41, v153
	v_lshl_add_u64 v[46:47], v[46:47], 0, v[40:41]
	v_add_co_u32_e32 v46, vcc, s96, v46
	s_nop 1
	v_addc_co_u32_e32 v47, vcc, 0, v47, vcc
	global_load_dwordx4 v[230:233], v[46:47], off offset:256
	v_lshl_add_u64 v[46:47], v[44:45], 0, v[30:31]
	v_mad_u64_u32 v[48:49], s[42:43], v46, s88, v[50:51]
	v_mov_b32_e32 v46, v49
	v_mad_u64_u32 v[46:47], s[42:43], v47, s88, v[46:47]
	v_mov_b32_e32 v49, v46
	v_lshl_add_u64 v[46:47], v[48:49], 0, v[38:39]
	v_lshl_add_u64 v[46:47], v[46:47], 0, v[40:41]
	v_add_co_u32_e32 v46, vcc, s96, v46
	s_nop 1
	v_addc_co_u32_e32 v47, vcc, 0, v47, vcc
	global_load_dwordx4 v[234:237], v[46:47], off offset:256
	s_waitcnt vmcnt(2)
	v_lshlrev_b32_e32 v37, 16, v226
	v_and_b32_e32 v39, 0xffff0000, v226
	v_lshlrev_b32_e32 v41, 16, v227
	v_and_b32_e32 v43, 0xffff0000, v227
	v_lshlrev_b32_e32 v46, 16, v228
	v_and_b32_e32 v47, 0xffff0000, v228
	v_lshlrev_b32_e32 v48, 16, v229
	v_and_b32_e32 v49, 0xffff0000, v229
	ds_write2_b32 v62, v37, v39 offset1:1
	ds_write2_b32 v62, v41, v43 offset0:2 offset1:3
	ds_write2_b32 v62, v46, v47 offset0:4 offset1:5
	ds_write2_b32 v62, v48, v49 offset0:6 offset1:7
	s_waitcnt vmcnt(1)
	v_lshlrev_b32_e32 v66, 16, v230
	v_and_b32_e32 v67, 0xffff0000, v230
	v_lshlrev_b32_e32 v68, 16, v231
	v_and_b32_e32 v69, 0xffff0000, v231
	v_lshlrev_b32_e32 v46, 16, v232
	v_and_b32_e32 v47, 0xffff0000, v232
	v_lshlrev_b32_e32 v48, 16, v233
	v_and_b32_e32 v49, 0xffff0000, v233
	ds_write_b128 v63, v[66:69] offset:8448
	ds_write_b128 v63, v[46:49] offset:8464
	s_waitcnt vmcnt(0)
	v_lshlrev_b32_e32 v244, 16, v234
	v_and_b32_e32 v245, 0xffff0000, v234
	v_lshlrev_b32_e32 v246, 16, v235
	v_and_b32_e32 v247, 0xffff0000, v235
	v_lshlrev_b32_e32 v248, 16, v236
	v_and_b32_e32 v249, 0xffff0000, v236
	v_lshlrev_b32_e32 v250, 16, v237
	v_and_b32_e32 v251, 0xffff0000, v237
	ds_write_b128 v65, v[244:247] offset:8448
	ds_write_b128 v65, v[248:251] offset:8464
	s_and_saveexec_b64 s[42:43], s[2:3]
	s_cbranch_execz .LBB0_432
	v_lshlrev_b32_e32 v48, 16, v238
	v_and_b32_e32 v49, 0xffff0000, v238
	v_lshlrev_b32_e32 v50, 16, v239
	v_and_b32_e32 v51, 0xffff0000, v239
	v_lshlrev_b32_e32 v44, 16, v240
	v_and_b32_e32 v45, 0xffff0000, v240
	v_lshlrev_b32_e32 v46, 16, v241
	v_and_b32_e32 v47, 0xffff0000, v241
	ds_write_b128 v59, v[48:51] offset:33280
	ds_write_b128 v59, v[44:47] offset:33296
